# MLA loop: K/KR LDS writes first, only they are drained before the second barrier (V tile writes complete later)
# speedup vs baseline: 1.0037x; 1.0001x over previous
.LBB0_762:
	ds_read_b128 v[64:67], v189 offset:49152
	ds_read_b128 v[68:71], v189 offset:57344
	ds_read_b128 v[236:239], v191 offset:49152
	ds_read_b128 v[240:243], v191 offset:57344
	ds_read_b128 v[244:247], v193 offset:49152
	ds_read_b128 v[248:251], v193 offset:57344
	s_add_i32 s9, s24, -1
	s_cmp_lt_u32 s9, 3
	s_cselect_b32 s100, s46, s68
	s_add_i32 s100, s100, s8
	s_ashr_i32 s101, s100, 31
	s_add_i32 s0, 0, 0x12800
	s_waitcnt lgkmcnt(5)
	v_mfma_f32_32x32x16_bf16 v[80:95], v[64:67], v[124:127], 0
	v_exp_f32_e32 v140, v140
	v_exp_f32_e32 v141, v141
	v_add_u32_e32 v211, s0, v198
	s_waitcnt lgkmcnt(4)
	v_mfma_f32_32x32x16_bf16 v[64:79], v[68:71], v[124:127], 0
	v_exp_f32_e32 v138, v138
	v_exp_f32_e32 v139, v139
	v_add_u32_e32 v210, s0, v200
	s_waitcnt lgkmcnt(3)
	v_mfma_f32_32x32x16_bf16 v[80:95], v[236:239], v[120:123], v[80:95]
	ds_read_b128 v[236:239], v195 offset:49152
	v_exp_f32_e32 v214, v130
	v_exp_f32_e32 v215, v131
	v_add_u32_e32 v216, s0, v202
	s_waitcnt lgkmcnt(3)
	v_mfma_f32_32x32x16_bf16 v[64:79], v[240:243], v[120:123], v[64:79]
	ds_read_b128 v[240:243], v195 offset:57344
	v_exp_f32_e32 v142, v142
	v_exp_f32_e32 v143, v143
	v_add_u32_e32 v217, s0, v204
	s_waitcnt lgkmcnt(3)
	v_mfma_f32_32x32x16_bf16 v[80:95], v[244:247], v[116:119], v[80:95]
	ds_read_b128 v[244:247], v196 offset:49152
	v_exp_f32_e32 v136, v136
	v_exp_f32_e32 v137, v137
	v_cvt_pk_bf16_f32 v130, v156, v158
	s_waitcnt lgkmcnt(3)
	v_mfma_f32_32x32x16_bf16 v[64:79], v[248:251], v[116:119], v[64:79]
	ds_read_b128 v[248:251], v196 offset:57344
	v_exp_f32_e32 v212, v132
	v_exp_f32_e32 v213, v133
	v_cvt_pk_bf16_f32 v131, v154, v155
	s_waitcnt lgkmcnt(3)
	v_mfma_f32_32x32x16_bf16 v[80:95], v[236:239], v[112:115], v[80:95]
	ds_read_b128 v[236:239], v194 offset:49152
	v_exp_f32_e32 v220, v128
	v_add_f32_e32 v128, 0, v159
	v_add_f32_e32 v128, v161, v128
	v_add_f32_e32 v128, v157, v128
	s_waitcnt lgkmcnt(3)
	v_mfma_f32_32x32x16_bf16 v[64:79], v[240:243], v[112:115], v[64:79]
	ds_read_b128 v[240:243], v194 offset:57344
	v_add_f32_e32 v128, v160, v128
	v_add_f32_e32 v128, v156, v128
	v_add_f32_e32 v128, v158, v128
	v_add_f32_e32 v128, v154, v128
	v_add_f32_e32 v128, v155, v128
	s_waitcnt lgkmcnt(3)
	v_mfma_f32_32x32x16_bf16 v[80:95], v[244:247], v[108:111], v[80:95]
	ds_read_b128 v[244:247], v192 offset:49152
	v_add_f32_e32 v128, v151, v128
	v_add_f32_e32 v128, v153, v128
	v_add_f32_e32 v128, v150, v128
	v_add_f32_e32 v128, v152, v128
	v_add_f32_e32 v128, v147, v128
	s_waitcnt lgkmcnt(3)
	v_mfma_f32_32x32x16_bf16 v[64:79], v[248:251], v[108:111], v[64:79]
	ds_read_b128 v[248:251], v192 offset:57344
	v_add_f32_e32 v128, v149, v128
	v_add_f32_e32 v128, v146, v128
	v_add_f32_e32 v128, v148, v128
	v_add_f32_e32 v128, v140, v128
	v_add_f32_e32 v128, v141, v128
	s_waitcnt lgkmcnt(3)
	v_mfma_f32_32x32x16_bf16 v[80:95], v[236:239], v[104:107], v[80:95]
	ds_read_b128 v[236:239], v190 offset:49152
	v_add_f32_e32 v128, v138, v128
	v_add_f32_e32 v128, v139, v128
	v_add_f32_e32 v128, v212, v128
	v_exp_f32_e32 v221, v129
	s_waitcnt lgkmcnt(3)
	v_mfma_f32_32x32x16_bf16 v[64:79], v[240:243], v[104:107], v[64:79]
	ds_read_b128 v[240:243], v190 offset:57344
	v_add_f32_e32 v128, v213, v128
	v_add_f32_e32 v128, v214, v128
	v_add_f32_e32 v128, v215, v128
	v_add_f32_e32 v128, v220, v128
	v_add_f32_e32 v128, v221, v128
	s_waitcnt lgkmcnt(3)
	v_mfma_f32_32x32x16_bf16 v[80:95], v[244:247], v[100:103], v[80:95]
	ds_read_b128 v[244:247], v211
	v_exp_f32_e32 v223, v134
	v_add_f32_e32 v128, v142, v128
	v_exp_f32_e32 v224, v135
	s_waitcnt lgkmcnt(3)
	v_mfma_f32_32x32x16_bf16 v[64:79], v[248:251], v[100:103], v[64:79]
	v_add_f32_e32 v128, v143, v128
	v_add_f32_e32 v128, v136, v128
	v_add_f32_e32 v128, v137, v128
	v_add_f32_e32 v128, v223, v128
	v_add_f32_e32 v218, v224, v128
	s_waitcnt lgkmcnt(2)
	v_mfma_f32_32x32x16_bf16 v[80:95], v[236:239], v[96:99], v[80:95]
	ds_read_b128 v[236:239], v211 offset:4096
	ds_read_b128 v[248:251], v182
	v_mov_b32_e32 v219, v218
	v_cvt_pk_bf16_f32 v128, v159, v161
	v_cvt_pk_bf16_f32 v129, v157, v160
	v_cvt_pk_bf16_f32 v132, v151, v153
	v_cvt_pk_bf16_f32 v133, v150, v152
	s_waitcnt lgkmcnt(3)
	v_mfma_f32_32x32x16_bf16 v[64:79], v[240:243], v[96:99], v[64:79]
	ds_read_b128 v[240:243], v210
	v_cvt_pk_bf16_f32 v134, v147, v149
	v_cvt_pk_bf16_f32 v135, v146, v148
	v_cvt_pk_bf16_f32 v154, v140, v141
	v_cvt_pk_bf16_f32 v155, v138, v139
	v_cvt_pk_bf16_f32 v156, v212, v213
	s_waitcnt lgkmcnt(1)
	v_mfma_f32_32x32x16_bf16 v[80:95], v[244:247], v[248:251], v[80:95]
	v_cvt_pk_bf16_f32 v157, v214, v215
	v_cvt_pk_bf16_f32 v220, v220, v221
	v_cvt_pk_bf16_f32 v221, v142, v143
	v_cvt_pk_bf16_f32 v222, v136, v137
	v_permlane32_swap_b32_e32 v218, v219
	v_mfma_f32_32x32x16_bf16 v[64:79], v[236:239], v[248:251], v[64:79]
	ds_read_b128 v[248:251], v210 offset:4096
	ds_read_b128 v[244:247], v182 offset:1024
	ds_read_b128 v[236:239], v216
	v_permlane32_swap_b32_e32 v128, v130
	v_cvt_pk_bf16_f32 v223, v223, v224
	v_permlane32_swap_b32_e32 v220, v222
	v_permlane32_swap_b32_e32 v129, v131
	v_permlane32_swap_b32_e32 v132, v134
	s_waitcnt lgkmcnt(1)
	v_mfma_f32_32x32x16_bf16 v[80:95], v[240:243], v[244:247], v[80:95]
	v_permlane32_swap_b32_e32 v133, v135
	v_permlane32_swap_b32_e32 v154, v156
	v_permlane32_swap_b32_e32 v155, v157
	v_permlane32_swap_b32_e32 v221, v223
	v_lshl_add_u64 v[136:137], s[100:101], 0, v[162:163]
	v_mfma_f32_32x32x16_bf16 v[64:79], v[248:251], v[244:247], v[64:79]
	ds_read_b128 v[244:247], v216 offset:4096
	ds_read_b128 v[240:243], v182 offset:2048
	ds_read_b128 v[248:251], v217
	v_mul_lo_u32 v138, v137, s40
	v_mul_lo_u32 v139, v136, s41
	v_mad_u64_u32 v[136:137], s[6:7], v136, s40, 0
	v_add3_u32 v137, v137, v139, v138
	v_lshl_add_u64 v[138:139], v[166:167], 0, s[100:101]
	s_waitcnt lgkmcnt(1)
	v_mfma_f32_32x32x16_bf16 v[80:95], v[236:239], v[240:243], v[80:95]
	v_mul_lo_u32 v140, v139, s40
	v_mul_lo_u32 v141, v138, s41
	v_mad_u64_u32 v[138:139], s[6:7], v138, s40, 0
	v_add3_u32 v139, v139, v141, v140
	v_lshlrev_b64 v[146:147], 1, v[136:137]
	v_mfma_f32_32x32x16_bf16 v[64:79], v[244:247], v[240:243], v[64:79]
	ds_read_b128 v[240:243], v217 offset:4096
	ds_read_b128 v[236:239], v182 offset:3072
	ds_read_b64_tr_b16 v[224:225], v181 offset:0
	ds_read_b64_tr_b16 v[226:227], v181 offset:0x800
	ds_read_b64_tr_b16 v[232:233], v181 offset:0x1000
	ds_read_b64_tr_b16 v[234:235], v181 offset:0x1800
	v_lshlrev_b64 v[148:149], 1, v[138:139]
	v_lshl_add_u64 v[158:159], s[100:101], 0, v[164:165]
	v_lshl_add_u64 v[136:137], v[168:169], 0, v[146:147]
	v_lshl_add_u64 v[140:141], v[168:169], 0, v[148:149]
	v_lshl_add_u64 v[146:147], v[170:171], 0, v[146:147]
	s_waitcnt lgkmcnt(4)
	v_mfma_f32_32x32x16_bf16 v[80:95], v[248:251], v[236:239], v[80:95]
	v_lshl_add_u64 v[150:151], v[170:171], 0, v[148:149]
	v_mad_u64_u32 v[160:161], s[100:101], v158, s3, v[172:173]
	v_mad_i32_i24 v161, v159, s3, v161
	v_mfma_f32_32x32x16_bf16 v[64:79], v[240:243], v[236:239], v[64:79]
	ds_read_b64_tr_b16 v[236:237], v181 offset:0x2000
	ds_read_b64_tr_b16 v[238:239], v181 offset:0x2800
	ds_read_b64_tr_b16 v[240:241], v181 offset:0x3000
	ds_read_b64_tr_b16 v[242:243], v181 offset:0x3800
	ds_read_b64_tr_b16 v[212:213], v181 offset:0x200
	ds_read_b64_tr_b16 v[214:215], v181 offset:0xa00
	global_load_dwordx4 v[136:139], v[136:137], off
	global_load_dwordx4 v[140:143], v[140:141], off
	global_load_dwordx4 v[146:149], v[146:147], off
	global_load_dwordx4 v[150:153], v[150:151], off
	global_load_dwordx4 v[158:161], v[160:161], off
	s_waitcnt lgkmcnt(8)
	v_mfma_f32_32x32x16_bf16 v[0:15], v[128:131], v[224:227], v[0:15]
	ds_read_b64_tr_b16 v[224:225], v181 offset:0x1200
	ds_read_b64_tr_b16 v[226:227], v181 offset:0x1a00
	v_max_f32_e32 v250, v81, v81
	v_max_f32_e32 v251, v80, v80
	v_max_f32_e32 v250, v251, v250
	v_max3_f32 v250, v250, v82, v83
	v_max3_f32 v250, v250, v84, v85
	s_waitcnt lgkmcnt(8)
	v_mfma_f32_32x32x16_bf16 v[0:15], v[132:135], v[232:235], v[0:15]
	ds_read_b64_tr_b16 v[232:233], v181 offset:0x2200
	ds_read_b64_tr_b16 v[234:235], v181 offset:0x2a00
	v_max3_f32 v250, v250, v86, v87
	v_max3_f32 v250, v250, v88, v89
	v_max3_f32 v250, v250, v90, v91
	v_max3_f32 v250, v250, v92, v93
	v_max3_f32 v250, v250, v94, v95
	s_waitcnt lgkmcnt(8)
	v_mfma_f32_32x32x16_bf16 v[0:15], v[154:157], v[236:239], v[0:15]
	ds_read_b64_tr_b16 v[236:237], v181 offset:0x3200
	ds_read_b64_tr_b16 v[238:239], v181 offset:0x3a00
	v_max3_f32 v250, v250, v64, v65
	v_max3_f32 v250, v250, v66, v67
	v_max3_f32 v250, v250, v68, v69
	v_max3_f32 v250, v250, v70, v71
	v_max3_f32 v250, v250, v72, v73
	s_waitcnt lgkmcnt(8)
	v_mfma_f32_32x32x16_bf16 v[0:15], v[220:223], v[240:243], v[0:15]
	ds_read_b64_tr_b16 v[240:241], v181 offset:0x400
	ds_read_b64_tr_b16 v[242:243], v181 offset:0xc00
	v_max3_f32 v250, v250, v74, v75
	v_max3_f32 v250, v250, v76, v77
	v_max3_f32 v250, v250, v78, v79
	v_mov_b32_e32 v251, v250
	s_nop 1
	v_permlane32_swap_b32_e32 v250, v251
	s_waitcnt lgkmcnt(8)
	v_mfma_f32_32x32x16_bf16 v[48:63], v[128:131], v[212:215], v[48:63]
	ds_read_b64_tr_b16 v[212:213], v181 offset:0x1400
	ds_read_b64_tr_b16 v[214:215], v181 offset:0x1c00
	v_max_f32_e32 v251, v251, v251
	v_max_f32_e32 v250, v250, v250
	v_max_f32_e32 v250, v250, v251
	v_sub_f32_e32 v251, v250, v207
	v_cmp_ge_f32_e32 vcc, s94, v251
	s_waitcnt lgkmcnt(8)
	v_mfma_f32_32x32x16_bf16 v[48:63], v[132:135], v[224:227], v[48:63]
	ds_read_b64_tr_b16 v[224:225], v181 offset:0x2400
	ds_read_b64_tr_b16 v[226:227], v181 offset:0x2c00
	v_max_f32_e32 v251, v207, v207
	v_max_f32_e32 v250, v251, v250
	v_sub_f32_e32 v251, v207, v250
	v_mul_f32_e32 v251, 0x3dd53b94, v251
	s_waitcnt lgkmcnt(8)
	v_mfma_f32_32x32x16_bf16 v[48:63], v[154:157], v[232:235], v[48:63]
	ds_read_b64_tr_b16 v[232:233], v181 offset:0x3400
	ds_read_b64_tr_b16 v[234:235], v181 offset:0x3c00
	v_exp_f32_e32 v251, v251
	s_waitcnt lgkmcnt(8)
	v_mfma_f32_32x32x16_bf16 v[48:63], v[220:223], v[236:239], v[48:63]
	ds_read_b64_tr_b16 v[236:237], v181 offset:0x600
	ds_read_b64_tr_b16 v[238:239], v181 offset:0xe00
	s_waitcnt lgkmcnt(8)
	v_mfma_f32_32x32x16_bf16 v[32:47], v[128:131], v[240:243], v[32:47]
	ds_read_b64_tr_b16 v[240:241], v181 offset:0x1600
	ds_read_b64_tr_b16 v[242:243], v181 offset:0x1e00
	s_waitcnt lgkmcnt(8)
	v_mfma_f32_32x32x16_bf16 v[32:47], v[132:135], v[212:215], v[32:47]
	ds_read_b64_tr_b16 v[212:213], v181 offset:0x2600
	ds_read_b64_tr_b16 v[214:215], v181 offset:0x2e00
	s_waitcnt lgkmcnt(8)
	v_mfma_f32_32x32x16_bf16 v[32:47], v[154:157], v[224:227], v[32:47]
	ds_read_b64_tr_b16 v[224:225], v181 offset:0x3600
	ds_read_b64_tr_b16 v[226:227], v181 offset:0x3e00
	s_waitcnt lgkmcnt(8)
	v_mfma_f32_32x32x16_bf16 v[32:47], v[220:223], v[232:235], v[32:47]
	s_waitcnt lgkmcnt(6)
	v_mfma_f32_32x32x16_bf16 v[16:31], v[128:131], v[236:239], v[16:31]
	s_waitcnt lgkmcnt(4)
	v_mfma_f32_32x32x16_bf16 v[16:31], v[132:135], v[240:243], v[16:31]
	s_waitcnt lgkmcnt(2)
	v_mfma_f32_32x32x16_bf16 v[16:31], v[154:157], v[212:215], v[16:31]
	s_waitcnt lgkmcnt(0)
	v_mfma_f32_32x32x16_bf16 v[16:31], v[220:223], v[224:227], v[16:31]
	s_cmp_eq_u64 vcc, exec
	s_cselect_b64 s[6:7], -1, 0
	s_barrier
	s_waitcnt vmcnt(0)
	v_cndmask_b32_e64 v220, v251, 1.0, s[6:7]
	v_add_u32_e32 v129, 0x10800, v208
	v_cmp_gt_f32_e32 vcc, 1.0, v220
	ds_write_b128 v187, v[146:149] offset:32768
	ds_write_b128 v188, v[150:153] offset:32768
	ds_write_b128 v129, v[158:161]
	ds_write_b128 v185, v[136:139]
	ds_write_b128 v186, v[140:143]
	s_nop 0
	s_nop 0
	s_nop 0
	s_nop 0
	s_nop 0
	s_cbranch_vccz .LBB0_766
	s_and_saveexec_b64 s[0:1], s[4:5]
	ds_write_b32 v183, v220 offset:128
	s_or_b64 exec, exec, s[0:1]
	s_waitcnt lgkmcnt(0)
	v_add_u32_e32 v129, v180, v144
	ds_read_b128 v[130:133], v129 offset:224
	ds_read_b128 v[134:137], v129 offset:192
	ds_read_b128 v[138:141], v129 offset:160
	ds_read_b128 v[146:149], v129 offset:128
	s_waitcnt lgkmcnt(3)
	v_pk_mul_f32 v[12:13], v[12:13], v[130:131]
	s_waitcnt lgkmcnt(2)
	v_pk_mul_f32 v[8:9], v[8:9], v[134:135]
	s_waitcnt lgkmcnt(1)
	v_pk_mul_f32 v[4:5], v[4:5], v[138:139]
	v_pk_mul_f32 v[14:15], v[14:15], v[132:133]
	v_pk_mul_f32 v[10:11], v[10:11], v[136:137]
	v_pk_mul_f32 v[6:7], v[6:7], v[140:141]
	s_waitcnt lgkmcnt(0)
	v_pk_mul_f32 v[2:3], v[2:3], v[148:149]
	v_pk_mul_f32 v[0:1], v[0:1], v[146:147]
	v_pk_mul_f32 v[60:61], v[60:61], v[130:131]
	v_pk_mul_f32 v[56:57], v[56:57], v[134:135]
	v_pk_mul_f32 v[52:53], v[52:53], v[138:139]
	v_pk_mul_f32 v[62:63], v[62:63], v[132:133]
	v_pk_mul_f32 v[58:59], v[58:59], v[136:137]
	v_pk_mul_f32 v[54:55], v[54:55], v[140:141]
	v_pk_mul_f32 v[50:51], v[50:51], v[148:149]
	v_pk_mul_f32 v[48:49], v[48:49], v[146:147]
	v_pk_mul_f32 v[44:45], v[44:45], v[130:131]
	v_pk_mul_f32 v[40:41], v[40:41], v[134:135]
	v_pk_mul_f32 v[36:37], v[36:37], v[138:139]
	v_pk_mul_f32 v[46:47], v[46:47], v[132:133]
	v_pk_mul_f32 v[42:43], v[42:43], v[136:137]
	v_pk_mul_f32 v[38:39], v[38:39], v[140:141]
	v_pk_mul_f32 v[34:35], v[34:35], v[148:149]
	v_pk_mul_f32 v[32:33], v[32:33], v[146:147]
	v_pk_mul_f32 v[28:29], v[28:29], v[130:131]
	v_pk_mul_f32 v[24:25], v[24:25], v[134:135]
	v_pk_mul_f32 v[20:21], v[20:21], v[138:139]
	v_pk_mul_f32 v[30:31], v[30:31], v[132:133]
	v_pk_mul_f32 v[26:27], v[26:27], v[136:137]
	v_pk_mul_f32 v[22:23], v[22:23], v[140:141]
	v_pk_mul_f32 v[18:19], v[18:19], v[148:149]
	v_pk_mul_f32 v[16:17], v[16:17], v[146:147]
.LBB0_766:
	v_cndmask_b32_e64 v207, v250, v207, s[6:7]
	v_mul_f32_e32 v146, 0xbdd53b94, v207
	v_fmamk_f32 v80, v80, 0x3dd53b94, v146
	v_exp_f32_e32 v128, v80
	v_fmamk_f32 v81, v81, 0x3dd53b94, v146
	v_fmamk_f32 v82, v82, 0x3dd53b94, v146
	v_fmamk_f32 v83, v83, 0x3dd53b94, v146
	v_fmamk_f32 v84, v84, 0x3dd53b94, v146
	v_fmamk_f32 v85, v85, 0x3dd53b94, v146
	v_fmamk_f32 v86, v86, 0x3dd53b94, v146
	v_fmamk_f32 v87, v87, 0x3dd53b94, v146
	v_fmamk_f32 v88, v88, 0x3dd53b94, v146
	v_fmamk_f32 v89, v89, 0x3dd53b94, v146
	v_fmamk_f32 v90, v90, 0x3dd53b94, v146
	v_fmamk_f32 v91, v91, 0x3dd53b94, v146
	v_fmamk_f32 v92, v92, 0x3dd53b94, v146
	v_fmamk_f32 v93, v93, 0x3dd53b94, v146
	v_fmamk_f32 v94, v94, 0x3dd53b94, v146
	v_fmamk_f32 v95, v95, 0x3dd53b94, v146
	v_fmamk_f32 v155, v64, 0x3dd53b94, v146
	v_fmamk_f32 v156, v65, 0x3dd53b94, v146
	v_fmamk_f32 v157, v66, 0x3dd53b94, v146
	v_fmamk_f32 v158, v67, 0x3dd53b94, v146
	v_fmamk_f32 v159, v68, 0x3dd53b94, v146
	v_fmamk_f32 v148, v69, 0x3dd53b94, v146
	v_fmamk_f32 v149, v70, 0x3dd53b94, v146
	v_fmamk_f32 v150, v71, 0x3dd53b94, v146
	v_fmamk_f32 v151, v72, 0x3dd53b94, v146
	v_fmamk_f32 v152, v73, 0x3dd53b94, v146
	v_fmamk_f32 v153, v74, 0x3dd53b94, v146
	v_fmamk_f32 v154, v75, 0x3dd53b94, v146
	v_fmamk_f32 v147, v76, 0x3dd53b94, v146
	v_exp_f32_e32 v143, v81
	v_exp_f32_e32 v129, v82
	v_exp_f32_e32 v142, v83
	v_exp_f32_e32 v130, v84
	v_exp_f32_e32 v141, v85
	v_exp_f32_e32 v131, v86
	v_exp_f32_e32 v140, v87
	v_exp_f32_e32 v132, v88
	v_exp_f32_e32 v139, v89
	v_exp_f32_e32 v133, v90
	v_exp_f32_e32 v138, v91
	v_exp_f32_e32 v134, v92
	v_exp_f32_e32 v137, v93
	v_exp_f32_e32 v135, v94
	v_exp_f32_e32 v136, v95
	v_fmamk_f32 v160, v77, 0x3dd53b94, v146
	v_fmamk_f32 v161, v78, 0x3dd53b94, v146
	v_fmac_f32_e32 v146, 0x3dd53b94, v79
	s_waitcnt lgkmcnt(2)
	s_barrier
	ds_read_b128 v[64:67], v189 offset:32768
	ds_read_b128 v[68:71], v189 offset:40960
	ds_read_b128 v[240:243], v191 offset:32768
	ds_read_b128 v[244:247], v191 offset:40960
	ds_read_b128 v[248:251], v193 offset:32768
	s_cmp_lt_u32 s9, 2
	s_cselect_b32 s100, s46, s68
	s_add_i32 s100, s100, s8
	s_add_i32 s100, s100, 64
	s_ashr_i32 s101, s100, 31
	s_waitcnt lgkmcnt(4)
	v_mfma_f32_32x32x16_bf16 v[80:95], v[64:67], v[124:127], 0
	v_exp_f32_e32 v212, v154
	v_add_f32_e32 v154, 0, v128
	v_add_f32_e32 v154, v143, v154
	v_add_f32_e32 v154, v129, v154
	s_waitcnt lgkmcnt(3)
	v_mfma_f32_32x32x16_bf16 v[64:79], v[68:71], v[124:127], 0
	v_add_f32_e32 v154, v142, v154
	v_add_f32_e32 v154, v130, v154
	v_add_f32_e32 v154, v141, v154
	v_add_f32_e32 v154, v131, v154
	v_add_f32_e32 v154, v140, v154
	s_waitcnt lgkmcnt(2)
	v_mfma_f32_32x32x16_bf16 v[80:95], v[240:243], v[120:123], v[80:95]
	ds_read_b128 v[240:243], v193 offset:40960
	v_add_f32_e32 v154, v132, v154
	v_add_f32_e32 v154, v139, v154
	v_add_f32_e32 v154, v133, v154
	v_add_f32_e32 v154, v138, v154
	v_add_f32_e32 v154, v134, v154
	s_waitcnt lgkmcnt(2)
	v_mfma_f32_32x32x16_bf16 v[64:79], v[244:247], v[120:123], v[64:79]
	ds_read_b128 v[244:247], v195 offset:32768
	v_exp_f32_e32 v155, v155
	v_exp_f32_e32 v156, v156
	v_add_f32_e32 v154, v137, v154
	s_waitcnt lgkmcnt(2)
	v_mfma_f32_32x32x16_bf16 v[80:95], v[248:251], v[116:119], v[80:95]
	ds_read_b128 v[248:251], v195 offset:40960
	v_exp_f32_e32 v157, v157
	v_add_f32_e32 v154, v135, v154
	v_exp_f32_e32 v158, v158
	s_waitcnt lgkmcnt(2)
	v_mfma_f32_32x32x16_bf16 v[64:79], v[240:243], v[116:119], v[64:79]
	ds_read_b128 v[240:243], v196 offset:32768
	v_add_f32_e32 v154, v136, v154
	v_exp_f32_e32 v159, v159
	v_add_f32_e32 v154, v155, v154
	v_add_f32_e32 v154, v156, v154
	s_waitcnt lgkmcnt(2)
	v_mfma_f32_32x32x16_bf16 v[80:95], v[244:247], v[112:115], v[80:95]
	ds_read_b128 v[244:247], v196 offset:40960
	v_exp_f32_e32 v148, v148
	v_exp_f32_e32 v149, v149
	v_add_f32_e32 v154, v157, v154
	s_waitcnt lgkmcnt(2)
	v_mfma_f32_32x32x16_bf16 v[64:79], v[248:251], v[112:115], v[64:79]
	ds_read_b128 v[248:251], v194 offset:32768
	v_exp_f32_e32 v150, v150
	v_add_f32_e32 v154, v158, v154
	v_exp_f32_e32 v151, v151
	s_waitcnt lgkmcnt(2)
	v_mfma_f32_32x32x16_bf16 v[80:95], v[240:243], v[108:111], v[80:95]
	ds_read_b128 v[240:243], v194 offset:40960
	v_add_f32_e32 v154, v159, v154
	v_exp_f32_e32 v152, v152
	v_add_f32_e32 v154, v148, v154
	v_add_f32_e32 v154, v149, v154
	s_waitcnt lgkmcnt(2)
	v_mfma_f32_32x32x16_bf16 v[64:79], v[244:247], v[108:111], v[64:79]
	ds_read_b128 v[244:247], v192 offset:32768
	v_exp_f32_e32 v153, v153
	v_add_f32_e32 v154, v150, v154
	v_exp_f32_e32 v147, v147
	s_waitcnt lgkmcnt(2)
	v_mfma_f32_32x32x16_bf16 v[80:95], v[248:251], v[104:107], v[80:95]
	ds_read_b128 v[248:251], v192 offset:40960
	v_add_f32_e32 v154, v151, v154
	v_exp_f32_e32 v160, v160
	v_add_f32_e32 v154, v152, v154
	v_add_f32_e32 v154, v153, v154
	s_waitcnt lgkmcnt(2)
	v_mfma_f32_32x32x16_bf16 v[64:79], v[240:243], v[104:107], v[64:79]
	ds_read_b128 v[240:243], v190 offset:32768
	v_exp_f32_e32 v161, v161
	v_exp_f32_e32 v146, v146
	v_add_f32_e32 v154, v212, v154
	s_waitcnt lgkmcnt(2)
	v_mfma_f32_32x32x16_bf16 v[80:95], v[244:247], v[100:103], v[80:95]
	ds_read_b128 v[244:247], v190 offset:40960
	v_add_f32_e32 v154, v147, v154
	v_add_f32_e32 v154, v160, v154
	v_add_f32_e32 v154, v161, v154
	v_cvt_pk_bf16_f32 v128, v128, v143
	v_cvt_pk_bf16_f32 v129, v129, v142
	s_waitcnt lgkmcnt(2)
	v_mfma_f32_32x32x16_bf16 v[64:79], v[248:251], v[100:103], v[64:79]
	ds_read_b128 v[248:251], v199
	v_cvt_pk_bf16_f32 v130, v130, v141
	v_cvt_pk_bf16_f32 v131, v131, v140
	v_cvt_pk_bf16_f32 v132, v132, v139
	v_cvt_pk_bf16_f32 v133, v133, v138
	v_add_f32_e32 v222, v146, v154
	s_waitcnt lgkmcnt(2)
	v_mfma_f32_32x32x16_bf16 v[80:95], v[240:243], v[96:99], v[80:95]
	v_mov_b32_e32 v223, v222
	s_nop 1
	v_permlane32_swap_b32_e32 v222, v223
	v_permlane32_swap_b32_e32 v128, v130
	v_cvt_pk_bf16_f32 v134, v134, v137
	v_cvt_pk_bf16_f32 v135, v135, v136
	s_waitcnt lgkmcnt(1)
	v_mfma_f32_32x32x16_bf16 v[64:79], v[244:247], v[96:99], v[64:79]
	ds_read_b128 v[244:247], v199 offset:4096
	ds_read_b128 v[240:243], v182
	v_cvt_pk_bf16_f32 v154, v155, v156
	v_cvt_pk_bf16_f32 v155, v157, v158
	v_cvt_pk_bf16_f32 v156, v159, v148
	v_cvt_pk_bf16_f32 v157, v149, v150
	v_cvt_pk_bf16_f32 v224, v151, v152
	s_waitcnt lgkmcnt(0)
	v_mfma_f32_32x32x16_bf16 v[80:95], v[248:251], v[240:243], v[80:95]
	ds_read_b128 v[248:251], v201
	v_cvt_pk_bf16_f32 v225, v153, v212
	v_cvt_pk_bf16_f32 v226, v147, v160
	v_cvt_pk_bf16_f32 v227, v161, v146
	v_permlane32_swap_b32_e32 v129, v131
	v_permlane32_swap_b32_e32 v132, v134
	v_mfma_f32_32x32x16_bf16 v[64:79], v[244:247], v[240:243], v[64:79]
	ds_read_b128 v[244:247], v201 offset:4096
	ds_read_b128 v[240:243], v182 offset:1024
	v_permlane32_swap_b32_e32 v133, v135
	v_permlane32_swap_b32_e32 v154, v156
	v_permlane32_swap_b32_e32 v155, v157
	v_permlane32_swap_b32_e32 v224, v226
	v_permlane32_swap_b32_e32 v225, v227
	s_waitcnt lgkmcnt(0)
	v_mfma_f32_32x32x16_bf16 v[80:95], v[248:251], v[240:243], v[80:95]
	ds_read_b128 v[248:251], v203
	v_lshl_add_u64 v[136:137], s[100:101], 0, v[162:163]
	v_mul_lo_u32 v138, v137, s40
	v_mul_lo_u32 v139, v136, s41
	v_mad_u64_u32 v[136:137], s[6:7], v136, s40, 0
	v_add3_u32 v137, v137, v139, v138
	v_mfma_f32_32x32x16_bf16 v[64:79], v[244:247], v[240:243], v[64:79]
	ds_read_b128 v[244:247], v203 offset:4096
	ds_read_b128 v[240:243], v182 offset:2048
	v_lshl_add_u64 v[138:139], v[166:167], 0, s[100:101]
	v_mul_lo_u32 v140, v139, s40
	v_mul_lo_u32 v141, v138, s41
	v_mad_u64_u32 v[138:139], s[6:7], v138, s40, 0
	v_add3_u32 v139, v139, v141, v140
	s_waitcnt lgkmcnt(0)
	v_mfma_f32_32x32x16_bf16 v[80:95], v[248:251], v[240:243], v[80:95]
	ds_read_b128 v[248:251], v205
	v_lshlrev_b64 v[146:147], 1, v[136:137]
	v_lshlrev_b64 v[148:149], 1, v[138:139]
	v_lshl_add_u64 v[158:159], s[100:101], 0, v[164:165]
	v_lshl_add_u64 v[136:137], v[168:169], 0, v[146:147]
	v_lshl_add_u64 v[140:141], v[168:169], 0, v[148:149]
	v_mfma_f32_32x32x16_bf16 v[64:79], v[244:247], v[240:243], v[64:79]
	ds_read_b128 v[244:247], v205 offset:4096
	ds_read_b128 v[240:243], v182 offset:3072
	ds_read_b64_tr_b16 v[232:233], v184 offset:0
	ds_read_b64_tr_b16 v[234:235], v184 offset:0x800
	ds_read_b64_tr_b16 v[236:237], v184 offset:0x1000
	ds_read_b64_tr_b16 v[238:239], v184 offset:0x1800
	v_lshl_add_u64 v[146:147], v[170:171], 0, v[146:147]
	v_lshl_add_u64 v[150:151], v[170:171], 0, v[148:149]
	v_mad_u64_u32 v[160:161], s[100:101], v158, s3, v[172:173]
	v_mad_i32_i24 v161, v159, s3, v161
	s_waitcnt lgkmcnt(4)
	v_mfma_f32_32x32x16_bf16 v[80:95], v[248:251], v[240:243], v[80:95]
	v_mfma_f32_32x32x16_bf16 v[64:79], v[244:247], v[240:243], v[64:79]
	ds_read_b64_tr_b16 v[240:241], v184 offset:0x2000
	ds_read_b64_tr_b16 v[242:243], v184 offset:0x2800
	ds_read_b64_tr_b16 v[244:245], v184 offset:0x3000
	ds_read_b64_tr_b16 v[246:247], v184 offset:0x3800
	global_load_dwordx4 v[136:139], v[136:137], off
	global_load_dwordx4 v[140:143], v[140:141], off
	global_load_dwordx4 v[146:149], v[146:147], off
	global_load_dwordx4 v[150:153], v[150:151], off
	global_load_dwordx4 v[158:161], v[160:161], off
	s_waitcnt lgkmcnt(6)
	v_mfma_f32_32x32x16_bf16 v[0:15], v[128:131], v[232:235], v[0:15]
	ds_read_b64_tr_b16 v[232:233], v184 offset:0x200
	ds_read_b64_tr_b16 v[234:235], v184 offset:0xa00
	s_waitcnt lgkmcnt(6)
	v_mfma_f32_32x32x16_bf16 v[0:15], v[132:135], v[236:239], v[0:15]
	ds_read_b64_tr_b16 v[236:237], v184 offset:0x1200
	ds_read_b64_tr_b16 v[238:239], v184 offset:0x1a00
	v_max_f32_e32 v250, v81, v81
	v_max_f32_e32 v251, v80, v80
	v_max_f32_e32 v250, v251, v250
	v_max3_f32 v250, v250, v82, v83
	v_max3_f32 v250, v250, v84, v85
	s_waitcnt lgkmcnt(6)
	v_mfma_f32_32x32x16_bf16 v[0:15], v[154:157], v[240:243], v[0:15]
	ds_read_b64_tr_b16 v[240:241], v184 offset:0x2200
	ds_read_b64_tr_b16 v[242:243], v184 offset:0x2a00
	v_max3_f32 v250, v250, v86, v87
	v_max3_f32 v250, v250, v88, v89
	v_max3_f32 v250, v250, v90, v91
	v_max3_f32 v250, v250, v92, v93
	v_max3_f32 v250, v250, v94, v95
	s_waitcnt lgkmcnt(6)
	v_mfma_f32_32x32x16_bf16 v[0:15], v[224:227], v[244:247], v[0:15]
	ds_read_b64_tr_b16 v[244:245], v184 offset:0x3200
	ds_read_b64_tr_b16 v[246:247], v184 offset:0x3a00
	v_max3_f32 v250, v250, v64, v65
	v_max3_f32 v250, v250, v66, v67
	v_max3_f32 v250, v250, v68, v69
	v_max3_f32 v250, v250, v70, v71
	v_max3_f32 v250, v250, v72, v73
	s_waitcnt lgkmcnt(6)
	v_mfma_f32_32x32x16_bf16 v[48:63], v[128:131], v[232:235], v[48:63]
	ds_read_b64_tr_b16 v[232:233], v184 offset:0x400
	ds_read_b64_tr_b16 v[234:235], v184 offset:0xc00
	v_max3_f32 v250, v250, v74, v75
	v_max3_f32 v250, v250, v76, v77
	v_max3_f32 v250, v250, v78, v79
	v_mov_b32_e32 v251, v250
	s_nop 1
	v_permlane32_swap_b32_e32 v250, v251
	s_waitcnt lgkmcnt(6)
	v_mfma_f32_32x32x16_bf16 v[48:63], v[132:135], v[236:239], v[48:63]
	ds_read_b64_tr_b16 v[236:237], v184 offset:0x1400
	ds_read_b64_tr_b16 v[238:239], v184 offset:0x1c00
	v_max_f32_e32 v251, v251, v251
	v_max_f32_e32 v250, v250, v250
	v_max_f32_e32 v250, v250, v251
	v_sub_f32_e32 v251, v250, v207
	v_cmp_ge_f32_e32 vcc, s94, v251
	s_waitcnt lgkmcnt(6)
	v_mfma_f32_32x32x16_bf16 v[48:63], v[154:157], v[240:243], v[48:63]
	ds_read_b64_tr_b16 v[240:241], v184 offset:0x2400
	ds_read_b64_tr_b16 v[242:243], v184 offset:0x2c00
	v_max_f32_e32 v251, v207, v207
	v_max_f32_e32 v250, v251, v250
	v_sub_f32_e32 v251, v207, v250
	v_mul_f32_e32 v251, 0x3dd53b94, v251
	s_waitcnt lgkmcnt(6)
	v_mfma_f32_32x32x16_bf16 v[48:63], v[224:227], v[244:247], v[48:63]
	ds_read_b64_tr_b16 v[244:245], v184 offset:0x3400
	ds_read_b64_tr_b16 v[246:247], v184 offset:0x3c00
	v_exp_f32_e32 v251, v251
	s_waitcnt lgkmcnt(6)
	v_mfma_f32_32x32x16_bf16 v[32:47], v[128:131], v[232:235], v[32:47]
	ds_read_b64_tr_b16 v[232:233], v184 offset:0x600
	ds_read_b64_tr_b16 v[234:235], v184 offset:0xe00
	s_waitcnt lgkmcnt(6)
	v_mfma_f32_32x32x16_bf16 v[32:47], v[132:135], v[236:239], v[32:47]
	ds_read_b64_tr_b16 v[236:237], v184 offset:0x1600
	ds_read_b64_tr_b16 v[238:239], v184 offset:0x1e00
	s_waitcnt lgkmcnt(6)
	v_mfma_f32_32x32x16_bf16 v[32:47], v[154:157], v[240:243], v[32:47]
	ds_read_b64_tr_b16 v[240:241], v184 offset:0x2600
	ds_read_b64_tr_b16 v[242:243], v184 offset:0x2e00
	s_waitcnt lgkmcnt(6)
	v_mfma_f32_32x32x16_bf16 v[32:47], v[224:227], v[244:247], v[32:47]
	ds_read_b64_tr_b16 v[244:245], v184 offset:0x3600
	ds_read_b64_tr_b16 v[246:247], v184 offset:0x3e00
	s_waitcnt lgkmcnt(6)
	v_mfma_f32_32x32x16_bf16 v[16:31], v[128:131], v[232:235], v[16:31]
	s_waitcnt lgkmcnt(4)
	v_mfma_f32_32x32x16_bf16 v[16:31], v[132:135], v[236:239], v[16:31]
	s_waitcnt lgkmcnt(2)
	v_mfma_f32_32x32x16_bf16 v[16:31], v[154:157], v[240:243], v[16:31]
	s_waitcnt lgkmcnt(0)
	v_mfma_f32_32x32x16_bf16 v[16:31], v[224:227], v[244:247], v[16:31]
	s_cmp_eq_u64 vcc, exec
	s_cselect_b64 s[6:7], -1, 0
	s_barrier
	s_waitcnt vmcnt(0)
	v_cndmask_b32_e64 v221, v251, 1.0, s[6:7]
	v_cmp_gt_f32_e32 vcc, 1.0, v221
	ds_write_b128 v187, v[146:149] offset:49152
	ds_write_b128 v188, v[150:153] offset:49152
	ds_write_b128 v209, v[158:161]
	ds_write_b128 v185, v[136:139] offset:16384
	ds_write_b128 v186, v[140:143] offset:16384
	s_nop 0
	s_nop 0
	s_nop 0
	s_nop 0
	s_nop 0
	s_cbranch_vccz .LBB0_770
	s_and_saveexec_b64 s[0:1], s[4:5]
	ds_write_b32 v183, v221 offset:128
	s_or_b64 exec, exec, s[0:1]
	s_waitcnt lgkmcnt(0)
	v_add_u32_e32 v129, v180, v144
	ds_read_b128 v[130:133], v129 offset:224
	ds_read_b128 v[134:137], v129 offset:192
	ds_read_b128 v[138:141], v129 offset:160
	ds_read_b128 v[146:149], v129 offset:128
	s_waitcnt lgkmcnt(3)
	v_pk_mul_f32 v[12:13], v[12:13], v[130:131]
	s_waitcnt lgkmcnt(2)
	v_pk_mul_f32 v[8:9], v[8:9], v[134:135]
	s_waitcnt lgkmcnt(1)
	v_pk_mul_f32 v[4:5], v[4:5], v[138:139]
	v_pk_mul_f32 v[14:15], v[14:15], v[132:133]
	v_pk_mul_f32 v[10:11], v[10:11], v[136:137]
	v_pk_mul_f32 v[6:7], v[6:7], v[140:141]
	s_waitcnt lgkmcnt(0)
	v_pk_mul_f32 v[2:3], v[2:3], v[148:149]
	v_pk_mul_f32 v[0:1], v[0:1], v[146:147]
	v_pk_mul_f32 v[60:61], v[60:61], v[130:131]
	v_pk_mul_f32 v[56:57], v[56:57], v[134:135]
	v_pk_mul_f32 v[52:53], v[52:53], v[138:139]
	v_pk_mul_f32 v[62:63], v[62:63], v[132:133]
	v_pk_mul_f32 v[58:59], v[58:59], v[136:137]
	v_pk_mul_f32 v[54:55], v[54:55], v[140:141]
	v_pk_mul_f32 v[50:51], v[50:51], v[148:149]
	v_pk_mul_f32 v[48:49], v[48:49], v[146:147]
	v_pk_mul_f32 v[44:45], v[44:45], v[130:131]
	v_pk_mul_f32 v[40:41], v[40:41], v[134:135]
	v_pk_mul_f32 v[36:37], v[36:37], v[138:139]
	v_pk_mul_f32 v[46:47], v[46:47], v[132:133]
	v_pk_mul_f32 v[42:43], v[42:43], v[136:137]
	v_pk_mul_f32 v[38:39], v[38:39], v[140:141]
	v_pk_mul_f32 v[34:35], v[34:35], v[148:149]
	v_pk_mul_f32 v[32:33], v[32:33], v[146:147]
	v_pk_mul_f32 v[28:29], v[28:29], v[130:131]
	v_pk_mul_f32 v[24:25], v[24:25], v[134:135]
	v_pk_mul_f32 v[20:21], v[20:21], v[138:139]
	v_pk_mul_f32 v[30:31], v[30:31], v[132:133]
	v_pk_mul_f32 v[26:27], v[26:27], v[136:137]
	v_pk_mul_f32 v[22:23], v[22:23], v[140:141]
	v_pk_mul_f32 v[18:19], v[18:19], v[148:149]
	v_pk_mul_f32 v[16:17], v[16:17], v[146:147]
.LBB0_770:
	v_cndmask_b32_e64 v207, v250, v207, s[6:7]
	v_mul_f32_e32 v134, 0xbdd53b94, v207
	v_mov_b32_e32 v135, v134
	v_fmamk_f32 v80, v80, 0x3dd53b94, v134
	v_fmamk_f32 v81, v81, 0x3dd53b94, v134
	v_fmamk_f32 v82, v82, 0x3dd53b94, v134
	v_fmamk_f32 v83, v83, 0x3dd53b94, v134
	v_fmamk_f32 v84, v84, 0x3dd53b94, v134
	v_fmamk_f32 v85, v85, 0x3dd53b94, v134
	v_fmamk_f32 v86, v86, 0x3dd53b94, v134
	v_fmamk_f32 v87, v87, 0x3dd53b94, v134
	v_fmamk_f32 v88, v88, 0x3dd53b94, v134
	v_fmamk_f32 v89, v89, 0x3dd53b94, v134
	v_fmamk_f32 v90, v90, 0x3dd53b94, v134
	v_fmamk_f32 v91, v91, 0x3dd53b94, v134
	v_fmamk_f32 v92, v92, 0x3dd53b94, v134
	v_fmamk_f32 v93, v93, 0x3dd53b94, v134
	v_fmamk_f32 v94, v94, 0x3dd53b94, v134
	v_fmac_f32_e32 v135, 0x3dd53b94, v95
	v_exp_f32_e32 v159, v80
	v_exp_f32_e32 v161, v81
	v_exp_f32_e32 v157, v82
	v_exp_f32_e32 v160, v83
	v_exp_f32_e32 v156, v84
	v_exp_f32_e32 v158, v85
	v_exp_f32_e32 v154, v86
	v_exp_f32_e32 v155, v87
	v_exp_f32_e32 v151, v88
	v_exp_f32_e32 v153, v89
	v_exp_f32_e32 v150, v90
	v_exp_f32_e32 v152, v91
	v_exp_f32_e32 v147, v92
	v_exp_f32_e32 v149, v93
	v_exp_f32_e32 v146, v94
	v_exp_f32_e32 v148, v135
	v_pk_fma_f32 v[140:141], v[64:65], s[76:77], v[134:135] op_sel_hi:[1,0,0]
	v_add_f32_e32 v64, v218, v219
	v_fmac_f32_e32 v64, v206, v197
	v_add_f32_e32 v197, v222, v223
	s_addk_i32 s8, 0x80
	s_add_i32 s24, s24, 2
	v_pk_fma_f32 v[138:139], v[66:67], s[76:77], v[134:135] op_sel_hi:[1,0,0]
	v_pk_fma_f32 v[132:133], v[68:69], s[76:77], v[134:135] op_sel_hi:[1,0,0]
	v_pk_fma_f32 v[130:131], v[70:71], s[76:77], v[134:135] op_sel_hi:[1,0,0]
	v_pk_fma_f32 v[128:129], v[72:73], s[76:77], v[134:135] op_sel_hi:[1,0,0]
	v_pk_fma_f32 v[142:143], v[74:75], s[76:77], v[134:135] op_sel_hi:[1,0,0]
	v_pk_fma_f32 v[136:137], v[76:77], s[76:77], v[134:135] op_sel_hi:[1,0,0]
	v_pk_fma_f32 v[134:135], v[78:79], s[76:77], v[134:135] op_sel_hi:[1,0,0]
	v_fmac_f32_e32 v197, v64, v220
	s_cmp_ge_u32 s24, s91
	s_waitcnt lgkmcnt(2)
	s_barrier
	s_cbranch_scc1 .LBB0_772
	v_mov_b32_e32 v206, v221
	s_branch .LBB0_762
